# g8 + first-add fold in window attention loop (8 sites, bit-exact)
# speedup vs baseline: 1.0096x; 1.0019x over previous
; DI float fexp2(float x) { return __builtin_amdgcn_exp2f(x); }
; DI void attn_core2(const u16* __restrict__ P, size_t tokbase, int kcol, int vcol, int n1, int n2, int xs0, bool win, int tq0,
;                    float m0, float l0, const bf16x8 (&qreg)[2][4], f32x16 (&o)[2][2], float (&lsum)[2], char* lds) {
;     ...
;         float la = 0.f;
;         if (mz[qs]) {
; #pragma unroll
;           for (int reg = 0; reg < 16; ++reg) { const float e = fexp2(pt[qs][reg]); pt[qs][reg] = e; la += e; }
;         } else {
; #pragma unroll
;           for (int reg = 0; reg < 16; ++reg) { const float e = fexp2(pt[qs][reg] - m[qs]); pt[qs][reg] = e; la += e; }
;         }
;         l[qs] += la;
;     ...
;   for (int it = 0; it < ntiles; it += 2) {
;     A_LOAD(kA, vA, it + 1);
;     compute(lds, it);
;     A_STORE(kA, vA, 1);
;     __syncthreads();
;     if (it + 2 < ntiles) A_LOAD(kA, vA, it + 2);
;     compute(lds + STAGE, it + 1);
;     if (it + 2 < ntiles) A_STORE(kA, vA, 0);
;     __syncthreads();
;   }
.LBB0_87:
	v_add_f32_e32 v0, v1, v0
	v_add_f32_e32 v1, v114, v113
	v_add_f32_e32 v0, v2, v0
	v_add_f32_e32 v1, v115, v1
	v_add_f32_e32 v0, v3, v0
	v_add_f32_e32 v1, v116, v1
	v_add_f32_e32 v0, v4, v0
	v_add_f32_e32 v1, v117, v1
	v_add_f32_e32 v0, v5, v0
	v_add_f32_e32 v1, v118, v1
	v_add_f32_e32 v0, v6, v0
	v_add_f32_e32 v1, v119, v1
	v_add_f32_e32 v0, v7, v0
	v_add_f32_e32 v1, v120, v1
	v_add_f32_e32 v0, v8, v0
	v_add_f32_e32 v1, v104, v1
	v_add_f32_e32 v1, v105, v1
	v_add_f32_e32 v0, v9, v0
	v_add_f32_e32 v1, v106, v1
	v_add_f32_e32 v0, v10, v0
	v_add_f32_e32 v1, v107, v1
	v_add_f32_e32 v0, v11, v0
	v_add_f32_e32 v1, v108, v1
	v_add_f32_e32 v0, v12, v0
	v_add_f32_e32 v1, v109, v1
	v_add_f32_e32 v0, v13, v0
	v_add_f32_e32 v1, v110, v1
	v_add_f32_e32 v0, v14, v0
	v_add_f32_e32 v1, v111, v1
	v_add_f32_e32 v0, v15, v0
	v_add_f32_e32 v185, v112, v1
	v_add_f32_e32 v79, v64, v0
	s_add_i32 s51, s51, 2
	s_addk_i32 s49, 0xff80
	s_andn2_b64 vcc, exec, s[42:43]
	s_addk_i32 s50, 0x80
	s_waitcnt lgkmcnt(0)
	s_barrier
	s_cbranch_vccz .LBB0_207

; DI float fexp2(float x) { return __builtin_amdgcn_exp2f(x); }
; DI float mx2(float a, float b) { return __builtin_elementwise_maximum(a, b); }
; DI float hmax(float v) { auto rr = __builtin_amdgcn_permlane32_swap(__float_as_uint(v), __float_as_uint(v), false, false); return mx2(__uint_as_float(rr[0]), __uint_as_float(rr[1])); }
; DI void attn_core2(const u16* __restrict__ P, size_t tokbase, int kcol, int vcol, int n1, int n2, int xs0, bool win, int tq0,
;                    float m0, float l0, const bf16x8 (&qreg)[2][4], f32x16 (&o)[2][2], float (&lsum)[2], char* lds) {
;     ...
;         float mloc = mx2(pt[qs][0], pt[qs][1]);
; #pragma unroll
;         for (int reg = 2; reg < 16; reg += 2) mloc = mx2(mx2(mloc, pt[qs][reg]), pt[qs][reg + 1]);
;         mloc = hmax(mloc) - m[qs];
;         if (__builtin_amdgcn_ballot_w64(mloc > THR) != 0) {
;           const float d = fmaxf(mloc, 0.f);
;           const float alpha = fexp2(-d);
;           m[qs] += d; l[qs] *= alpha; mz[qs] = false;
; #pragma unroll
;           for (int b = 0; b < 2; ++b)
; #pragma unroll
;             for (int reg = 0; reg < 16; ++reg) o[qs][b][reg] *= alpha;
;         }
;         float la = 0.f;
;         if (mz[qs]) {
; #pragma unroll
;           for (int reg = 0; reg < 16; ++reg) { const float e = fexp2(pt[qs][reg]); pt[qs][reg] = e; la += e; }
;         } else {
; #pragma unroll
;           for (int reg = 0; reg < 16; ++reg) { const float e = fexp2(pt[qs][reg] - m[qs]); pt[qs][reg] = e; la += e; }
;         }
;         l[qs] += la;
.LBB0_98:
	v_add_f32_e32 v0, v1, v0
	v_add_f32_e32 v0, v2, v0
	v_add_f32_e32 v0, v3, v0
	v_add_f32_e32 v0, v4, v0
	v_add_f32_e32 v0, v5, v0
	v_add_f32_e32 v0, v6, v0
	v_add_f32_e32 v0, v7, v0
	v_add_f32_e32 v0, v8, v0
	v_add_f32_e32 v0, v9, v0
	v_add_f32_e32 v0, v10, v0
	v_add_f32_e32 v0, v11, v0
	v_add_f32_e32 v0, v12, v0
	v_add_f32_e32 v0, v13, v0
	v_add_f32_e32 v0, v14, v0
	v_add_f32_e32 v0, v15, v0
	v_add_f32_e32 v186, v79, v0
	v_maximum3_f32 v0, v112, v113, v113
	v_maximum3_f32 v0, v0, v114, v115
	v_maximum3_f32 v0, v0, v116, v117
	v_maximum3_f32 v0, v0, v118, v119
	v_maximum3_f32 v0, v0, v120, v121
	v_maximum3_f32 v0, v0, v122, v123
	v_maximum3_f32 v0, v0, v124, v125
	v_maximum3_f32 v0, v0, v126, v127
	v_mov_b32_e32 v1, v0
	s_nop 1
	v_permlane32_swap_b32_e32 v0, v1
	v_maximum3_f32 v0, v0, v1, v1
	v_sub_f32_e32 v0, v0, v78
	v_cmp_lt_f32_e32 vcc, s76, v0
	s_cbranch_vccz .LBB0_100
	v_max_f32_e32 v0, v0, v0
	v_max_f32_e32 v1, 0, v0
	v_exp_f32_e64 v0, -v1
	v_add_f32_e32 v78, v78, v1
	v_mul_f32_e32 v186, v186, v0
	v_pk_mul_f32 v[94:95], v[94:95], v[0:1] op_sel_hi:[1,0]
	v_pk_mul_f32 v[92:93], v[92:93], v[0:1] op_sel_hi:[1,0]
	v_pk_mul_f32 v[90:91], v[90:91], v[0:1] op_sel_hi:[1,0]
	v_pk_mul_f32 v[88:89], v[88:89], v[0:1] op_sel_hi:[1,0]
	v_pk_mul_f32 v[86:87], v[86:87], v[0:1] op_sel_hi:[1,0]
	v_pk_mul_f32 v[84:85], v[84:85], v[0:1] op_sel_hi:[1,0]
	v_pk_mul_f32 v[82:83], v[82:83], v[0:1] op_sel_hi:[1,0]
	v_pk_mul_f32 v[80:81], v[80:81], v[0:1] op_sel_hi:[1,0]
	v_pk_mul_f32 v[62:63], v[62:63], v[0:1] op_sel_hi:[1,0]
	v_pk_mul_f32 v[60:61], v[60:61], v[0:1] op_sel_hi:[1,0]
	v_pk_mul_f32 v[58:59], v[58:59], v[0:1] op_sel_hi:[1,0]
	v_pk_mul_f32 v[56:57], v[56:57], v[0:1] op_sel_hi:[1,0]
	v_pk_mul_f32 v[54:55], v[54:55], v[0:1] op_sel_hi:[1,0]
	v_pk_mul_f32 v[52:53], v[52:53], v[0:1] op_sel_hi:[1,0]
	v_pk_mul_f32 v[50:51], v[50:51], v[0:1] op_sel_hi:[1,0]
	v_pk_mul_f32 v[48:49], v[48:49], v[0:1] op_sel_hi:[1,0]

; DI float fexp2(float x) { return __builtin_amdgcn_exp2f(x); }
; DI float mx2(float a, float b) { return __builtin_elementwise_maximum(a, b); }
; DI float hmax(float v) { auto rr = __builtin_amdgcn_permlane32_swap(__float_as_uint(v), __float_as_uint(v), false, false); return mx2(__uint_as_float(rr[0]), __uint_as_float(rr[1])); }
; DI void attn_core2(const u16* __restrict__ P, size_t tokbase, int kcol, int vcol, int n1, int n2, int xs0, bool win, int tq0,
;                    float m0, float l0, const bf16x8 (&qreg)[2][4], f32x16 (&o)[2][2], float (&lsum)[2], char* lds) {
;     ...
;         float mloc = mx2(pt[qs][0], pt[qs][1]);
; #pragma unroll
;         for (int reg = 2; reg < 16; reg += 2) mloc = mx2(mx2(mloc, pt[qs][reg]), pt[qs][reg + 1]);
;         mloc = hmax(mloc) - m[qs];
;         if (__builtin_amdgcn_ballot_w64(mloc > THR) != 0) {
;           const float d = fmaxf(mloc, 0.f);
;           const float alpha = fexp2(-d);
;           m[qs] += d; l[qs] *= alpha; mz[qs] = false;
; #pragma unroll
;           for (int b = 0; b < 2; ++b)
; #pragma unroll
;             for (int reg = 0; reg < 16; ++reg) o[qs][b][reg] *= alpha;
;         }
;         float la = 0.f;
;         if (mz[qs]) {
; #pragma unroll
;           for (int reg = 0; reg < 16; ++reg) { const float e = fexp2(pt[qs][reg]); pt[qs][reg] = e; la += e; }
;         } else {
; #pragma unroll
;           for (int reg = 0; reg < 16; ++reg) { const float e = fexp2(pt[qs][reg] - m[qs]); pt[qs][reg] = e; la += e; }
;         }
;         l[qs] += la;
.LBB0_102:
	v_add_f32_e32 v79, v188, v187
	v_add_f32_e32 v79, v189, v79
	v_add_f32_e32 v79, v214, v79
	v_add_f32_e32 v79, v215, v79
	v_add_f32_e32 v79, v216, v79
	v_add_f32_e32 v79, v217, v79
	v_add_f32_e32 v79, v218, v79
	v_add_f32_e32 v79, v219, v79
	v_add_f32_e32 v79, v220, v79
	v_add_f32_e32 v79, v221, v79
	v_add_f32_e32 v79, v222, v79
	v_add_f32_e32 v79, v223, v79
	v_add_f32_e32 v79, v224, v79
	v_add_f32_e32 v79, v225, v79
	v_add_f32_e32 v79, v226, v79
	v_add_f32_e32 v185, v185, v79
	v_maximum3_f32 v79, v96, v97, v97
	v_maximum3_f32 v79, v79, v98, v99
	v_maximum3_f32 v79, v79, v100, v101
	v_maximum3_f32 v79, v79, v102, v103
	v_maximum3_f32 v79, v79, v104, v105
	v_maximum3_f32 v79, v79, v106, v107
	v_maximum3_f32 v79, v79, v108, v109
	v_maximum3_f32 v79, v79, v110, v111
	v_mov_b32_e32 v112, v79
	s_nop 1
	v_permlane32_swap_b32_e32 v79, v112
	v_maximum3_f32 v79, v79, v112, v112
	v_sub_f32_e32 v79, v79, v174
	v_cmp_lt_f32_e32 vcc, s76, v79
	s_cbranch_vccz .LBB0_104
	v_max_f32_e32 v79, v79, v79
	v_max_f32_e32 v79, 0, v79
	v_exp_f32_e64 v112, -v79
	v_add_f32_e32 v174, v174, v79
	v_mul_f32_e32 v185, v185, v112
	v_pk_mul_f32 v[46:47], v[46:47], v[112:113] op_sel_hi:[1,0]
	v_pk_mul_f32 v[44:45], v[44:45], v[112:113] op_sel_hi:[1,0]
	v_pk_mul_f32 v[42:43], v[42:43], v[112:113] op_sel_hi:[1,0]
	v_pk_mul_f32 v[40:41], v[40:41], v[112:113] op_sel_hi:[1,0]
	v_pk_mul_f32 v[38:39], v[38:39], v[112:113] op_sel_hi:[1,0]
	v_pk_mul_f32 v[36:37], v[36:37], v[112:113] op_sel_hi:[1,0]
	v_pk_mul_f32 v[34:35], v[34:35], v[112:113] op_sel_hi:[1,0]
	v_pk_mul_f32 v[32:33], v[32:33], v[112:113] op_sel_hi:[1,0]
	v_pk_mul_f32 v[30:31], v[30:31], v[112:113] op_sel_hi:[1,0]
	v_pk_mul_f32 v[28:29], v[28:29], v[112:113] op_sel_hi:[1,0]
	v_pk_mul_f32 v[26:27], v[26:27], v[112:113] op_sel_hi:[1,0]
	v_pk_mul_f32 v[24:25], v[24:25], v[112:113] op_sel_hi:[1,0]
	v_pk_mul_f32 v[22:23], v[22:23], v[112:113] op_sel_hi:[1,0]
	v_pk_mul_f32 v[20:21], v[20:21], v[112:113] op_sel_hi:[1,0]
	v_pk_mul_f32 v[18:19], v[18:19], v[112:113] op_sel_hi:[1,0]
	v_pk_mul_f32 v[16:17], v[16:17], v[112:113] op_sel_hi:[1,0]

; DI float fexp2(float x) { return __builtin_amdgcn_exp2f(x); }
; DI float mx2(float a, float b) { return __builtin_elementwise_maximum(a, b); }
; DI float hmax(float v) { auto rr = __builtin_amdgcn_permlane32_swap(__float_as_uint(v), __float_as_uint(v), false, false); return mx2(__uint_as_float(rr[0]), __uint_as_float(rr[1])); }
; DI void attn_core2(const u16* __restrict__ P, size_t tokbase, int kcol, int vcol, int n1, int n2, int xs0, bool win, int tq0,
;                    float m0, float l0, const bf16x8 (&qreg)[2][4], f32x16 (&o)[2][2], float (&lsum)[2], char* lds) {
;     ...
;         float mloc = mx2(pt[qs][0], pt[qs][1]);
; #pragma unroll
;         for (int reg = 2; reg < 16; reg += 2) mloc = mx2(mx2(mloc, pt[qs][reg]), pt[qs][reg + 1]);
;         mloc = hmax(mloc) - m[qs];
;         if (__builtin_amdgcn_ballot_w64(mloc > THR) != 0) {
;           const float d = fmaxf(mloc, 0.f);
;           const float alpha = fexp2(-d);
;           m[qs] += d; l[qs] *= alpha; mz[qs] = false;
; #pragma unroll
;           for (int b = 0; b < 2; ++b)
; #pragma unroll
;             for (int reg = 0; reg < 16; ++reg) o[qs][b][reg] *= alpha;
;         }
;         float la = 0.f;
;         if (mz[qs]) {
; #pragma unroll
;           for (int reg = 0; reg < 16; ++reg) { const float e = fexp2(pt[qs][reg]); pt[qs][reg] = e; la += e; }
;         } else {
; #pragma unroll
;           for (int reg = 0; reg < 16; ++reg) { const float e = fexp2(pt[qs][reg] - m[qs]); pt[qs][reg] = e; la += e; }
;         }
;         l[qs] += la;
.LBB0_108:
	v_add_f32_e32 v0, v1, v0
	v_add_f32_e32 v0, v2, v0
	v_add_f32_e32 v0, v3, v0
	v_add_f32_e32 v0, v4, v0
	v_add_f32_e32 v0, v5, v0
	v_add_f32_e32 v0, v6, v0
	v_add_f32_e32 v0, v7, v0
	v_add_f32_e32 v0, v8, v0
	v_add_f32_e32 v0, v9, v0
	v_add_f32_e32 v0, v10, v0
	v_add_f32_e32 v0, v11, v0
	v_add_f32_e32 v0, v12, v0
	v_add_f32_e32 v0, v13, v0
	v_add_f32_e32 v0, v14, v0
	v_add_f32_e32 v0, v15, v0
	v_add_f32_e32 v64, v186, v0
	v_maximum3_f32 v0, v112, v113, v113
	v_maximum3_f32 v0, v0, v114, v115
	v_maximum3_f32 v0, v0, v116, v117
	v_maximum3_f32 v0, v0, v118, v119
	v_maximum3_f32 v0, v0, v120, v121
	v_maximum3_f32 v0, v0, v122, v123
	v_maximum3_f32 v0, v0, v124, v125
	v_maximum3_f32 v0, v0, v126, v127
	v_mov_b32_e32 v1, v0
	s_nop 1
	v_permlane32_swap_b32_e32 v0, v1
	v_maximum3_f32 v0, v0, v1, v1
	v_sub_f32_e32 v0, v0, v78
	v_cmp_lt_f32_e32 vcc, s76, v0
	s_cbranch_vccz .LBB0_110
	v_max_f32_e32 v0, v0, v0
	v_max_f32_e32 v1, 0, v0
	v_exp_f32_e64 v0, -v1
	v_add_f32_e32 v78, v78, v1
	v_mul_f32_e32 v64, v64, v0
	v_pk_mul_f32 v[94:95], v[94:95], v[0:1] op_sel_hi:[1,0]
	v_pk_mul_f32 v[92:93], v[92:93], v[0:1] op_sel_hi:[1,0]
	v_pk_mul_f32 v[90:91], v[90:91], v[0:1] op_sel_hi:[1,0]
	v_pk_mul_f32 v[88:89], v[88:89], v[0:1] op_sel_hi:[1,0]
	v_pk_mul_f32 v[86:87], v[86:87], v[0:1] op_sel_hi:[1,0]
	v_pk_mul_f32 v[84:85], v[84:85], v[0:1] op_sel_hi:[1,0]
	v_pk_mul_f32 v[82:83], v[82:83], v[0:1] op_sel_hi:[1,0]
	v_pk_mul_f32 v[80:81], v[80:81], v[0:1] op_sel_hi:[1,0]
	v_pk_mul_f32 v[62:63], v[62:63], v[0:1] op_sel_hi:[1,0]
	v_pk_mul_f32 v[60:61], v[60:61], v[0:1] op_sel_hi:[1,0]
	v_pk_mul_f32 v[58:59], v[58:59], v[0:1] op_sel_hi:[1,0]
	v_pk_mul_f32 v[56:57], v[56:57], v[0:1] op_sel_hi:[1,0]
	v_pk_mul_f32 v[54:55], v[54:55], v[0:1] op_sel_hi:[1,0]
	v_pk_mul_f32 v[52:53], v[52:53], v[0:1] op_sel_hi:[1,0]
	v_pk_mul_f32 v[50:51], v[50:51], v[0:1] op_sel_hi:[1,0]
	v_pk_mul_f32 v[48:49], v[48:49], v[0:1] op_sel_hi:[1,0]

; DI float fexp2(float x) { return __builtin_amdgcn_exp2f(x); }
; DI float mx2(float a, float b) { return __builtin_elementwise_maximum(a, b); }
; DI float hmax(float v) { auto rr = __builtin_amdgcn_permlane32_swap(__float_as_uint(v), __float_as_uint(v), false, false); return mx2(__uint_as_float(rr[0]), __uint_as_float(rr[1])); }
; DI void attn_core2(const u16* __restrict__ P, size_t tokbase, int kcol, int vcol, int n1, int n2, int xs0, bool win, int tq0,
;                    float m0, float l0, const bf16x8 (&qreg)[2][4], f32x16 (&o)[2][2], float (&lsum)[2], char* lds) {
;     ...
;         float mloc = mx2(pt[qs][0], pt[qs][1]);
; #pragma unroll
;         for (int reg = 2; reg < 16; reg += 2) mloc = mx2(mx2(mloc, pt[qs][reg]), pt[qs][reg + 1]);
;         mloc = hmax(mloc) - m[qs];
;         if (__builtin_amdgcn_ballot_w64(mloc > THR) != 0) {
;           const float d = fmaxf(mloc, 0.f);
;           const float alpha = fexp2(-d);
;           m[qs] += d; l[qs] *= alpha; mz[qs] = false;
; #pragma unroll
;           for (int b = 0; b < 2; ++b)
; #pragma unroll
;             for (int reg = 0; reg < 16; ++reg) o[qs][b][reg] *= alpha;
;         }
;         float la = 0.f;
;         if (mz[qs]) {
; #pragma unroll
;           for (int reg = 0; reg < 16; ++reg) { const float e = fexp2(pt[qs][reg]); pt[qs][reg] = e; la += e; }
;         } else {
; #pragma unroll
;           for (int reg = 0; reg < 16; ++reg) { const float e = fexp2(pt[qs][reg] - m[qs]); pt[qs][reg] = e; la += e; }
;         }
;         l[qs] += la;
.LBB0_112:
	v_add_f32_e32 v112, v188, v187
	v_add_f32_e32 v112, v189, v112
	v_add_f32_e32 v112, v214, v112
	v_add_f32_e32 v112, v215, v112
	v_add_f32_e32 v112, v216, v112
	v_add_f32_e32 v112, v217, v112
	v_add_f32_e32 v112, v218, v112
	v_add_f32_e32 v112, v219, v112
	v_add_f32_e32 v112, v220, v112
	v_add_f32_e32 v112, v221, v112
	v_add_f32_e32 v112, v222, v112
	v_add_f32_e32 v112, v223, v112
	v_add_f32_e32 v112, v224, v112
	v_add_f32_e32 v112, v225, v112
	v_add_f32_e32 v112, v226, v112
	v_add_f32_e32 v185, v185, v112
	v_maximum3_f32 v112, v96, v97, v97
	v_maximum3_f32 v112, v112, v98, v99
	v_maximum3_f32 v112, v112, v100, v101
	v_maximum3_f32 v112, v112, v102, v103
	v_maximum3_f32 v112, v112, v104, v105
	v_maximum3_f32 v112, v112, v106, v107
	v_maximum3_f32 v112, v112, v108, v109
	v_maximum3_f32 v112, v112, v110, v111
	v_mov_b32_e32 v113, v112
	s_nop 1
	v_permlane32_swap_b32_e32 v112, v113
	v_maximum3_f32 v112, v112, v113, v113
	v_sub_f32_e32 v112, v112, v174
	v_cmp_lt_f32_e32 vcc, s76, v112
	s_cbranch_vccz .LBB0_114
	v_max_f32_e32 v112, v112, v112
	v_max_f32_e32 v113, 0, v112
	v_exp_f32_e64 v112, -v113
	v_add_f32_e32 v174, v174, v113
	v_mul_f32_e32 v185, v185, v112
	v_pk_mul_f32 v[46:47], v[46:47], v[112:113] op_sel_hi:[1,0]
	v_pk_mul_f32 v[44:45], v[44:45], v[112:113] op_sel_hi:[1,0]
	v_pk_mul_f32 v[42:43], v[42:43], v[112:113] op_sel_hi:[1,0]
	v_pk_mul_f32 v[40:41], v[40:41], v[112:113] op_sel_hi:[1,0]
	v_pk_mul_f32 v[38:39], v[38:39], v[112:113] op_sel_hi:[1,0]
	v_pk_mul_f32 v[36:37], v[36:37], v[112:113] op_sel_hi:[1,0]
	v_pk_mul_f32 v[34:35], v[34:35], v[112:113] op_sel_hi:[1,0]
	v_pk_mul_f32 v[32:33], v[32:33], v[112:113] op_sel_hi:[1,0]
	v_pk_mul_f32 v[30:31], v[30:31], v[112:113] op_sel_hi:[1,0]
	v_pk_mul_f32 v[28:29], v[28:29], v[112:113] op_sel_hi:[1,0]
	v_pk_mul_f32 v[26:27], v[26:27], v[112:113] op_sel_hi:[1,0]
	v_pk_mul_f32 v[24:25], v[24:25], v[112:113] op_sel_hi:[1,0]
	v_pk_mul_f32 v[22:23], v[22:23], v[112:113] op_sel_hi:[1,0]
	v_pk_mul_f32 v[20:21], v[20:21], v[112:113] op_sel_hi:[1,0]
	v_pk_mul_f32 v[18:19], v[18:19], v[112:113] op_sel_hi:[1,0]
	v_pk_mul_f32 v[16:17], v[16:17], v[112:113] op_sel_hi:[1,0]

; DI float fexp2(float x) { return __builtin_amdgcn_exp2f(x); }
; DI float mx2(float a, float b) { return __builtin_elementwise_maximum(a, b); }
; DI float hmax(float v) { auto rr = __builtin_amdgcn_permlane32_swap(__float_as_uint(v), __float_as_uint(v), false, false); return mx2(__uint_as_float(rr[0]), __uint_as_float(rr[1])); }
; DI void attn_core2(const u16* __restrict__ P, size_t tokbase, int kcol, int vcol, int n1, int n2, int xs0, bool win, int tq0,
;                    float m0, float l0, const bf16x8 (&qreg)[2][4], f32x16 (&o)[2][2], float (&lsum)[2], char* lds) {
;     ...
;         float mloc = mx2(pt[qs][0], pt[qs][1]);
; #pragma unroll
;         for (int reg = 2; reg < 16; reg += 2) mloc = mx2(mx2(mloc, pt[qs][reg]), pt[qs][reg + 1]);
;         mloc = hmax(mloc) - m[qs];
;         if (__builtin_amdgcn_ballot_w64(mloc > THR) != 0) {
;           const float d = fmaxf(mloc, 0.f);
;           const float alpha = fexp2(-d);
;           m[qs] += d; l[qs] *= alpha; mz[qs] = false;
; #pragma unroll
;           for (int b = 0; b < 2; ++b)
; #pragma unroll
;             for (int reg = 0; reg < 16; ++reg) o[qs][b][reg] *= alpha;
;         }
;         float la = 0.f;
;         if (mz[qs]) {
; #pragma unroll
;           for (int reg = 0; reg < 16; ++reg) { const float e = fexp2(pt[qs][reg]); pt[qs][reg] = e; la += e; }
;         } else {
; #pragma unroll
;           for (int reg = 0; reg < 16; ++reg) { const float e = fexp2(pt[qs][reg] - m[qs]); pt[qs][reg] = e; la += e; }
;         }
;         l[qs] += la;
.LBB0_116:
	v_add_f32_e32 v0, v1, v0
	v_add_f32_e32 v0, v2, v0
	v_add_f32_e32 v0, v3, v0
	v_add_f32_e32 v0, v4, v0
	v_add_f32_e32 v0, v5, v0
	v_add_f32_e32 v0, v6, v0
	v_add_f32_e32 v0, v7, v0
	v_add_f32_e32 v0, v8, v0
	v_add_f32_e32 v0, v9, v0
	v_add_f32_e32 v0, v10, v0
	v_add_f32_e32 v0, v11, v0
	v_add_f32_e32 v0, v12, v0
	v_add_f32_e32 v0, v13, v0
	v_add_f32_e32 v0, v14, v0
	v_add_f32_e32 v0, v15, v0
	v_add_f32_e32 v64, v64, v0
	v_maximum3_f32 v0, v112, v113, v113
	v_maximum3_f32 v0, v0, v114, v115
	v_maximum3_f32 v0, v0, v116, v117
	v_maximum3_f32 v0, v0, v118, v119
	v_maximum3_f32 v0, v0, v120, v121
	v_maximum3_f32 v0, v0, v122, v123
	v_maximum3_f32 v0, v0, v124, v125
	v_maximum3_f32 v0, v0, v126, v127
	v_mov_b32_e32 v1, v0
	s_nop 1
	v_permlane32_swap_b32_e32 v0, v1
	v_maximum3_f32 v0, v0, v1, v1
	v_sub_f32_e32 v0, v0, v78
	v_cmp_lt_f32_e32 vcc, s76, v0
	s_cbranch_vccz .LBB0_118
	v_max_f32_e32 v0, v0, v0
	v_max_f32_e32 v1, 0, v0
	v_exp_f32_e64 v0, -v1
	v_add_f32_e32 v78, v78, v1
	v_mul_f32_e32 v64, v64, v0
	v_pk_mul_f32 v[94:95], v[94:95], v[0:1] op_sel_hi:[1,0]
	v_pk_mul_f32 v[92:93], v[92:93], v[0:1] op_sel_hi:[1,0]
	v_pk_mul_f32 v[90:91], v[90:91], v[0:1] op_sel_hi:[1,0]
	v_pk_mul_f32 v[88:89], v[88:89], v[0:1] op_sel_hi:[1,0]
	v_pk_mul_f32 v[86:87], v[86:87], v[0:1] op_sel_hi:[1,0]
	v_pk_mul_f32 v[84:85], v[84:85], v[0:1] op_sel_hi:[1,0]
	v_pk_mul_f32 v[82:83], v[82:83], v[0:1] op_sel_hi:[1,0]
	v_pk_mul_f32 v[80:81], v[80:81], v[0:1] op_sel_hi:[1,0]
	v_pk_mul_f32 v[62:63], v[62:63], v[0:1] op_sel_hi:[1,0]
	v_pk_mul_f32 v[60:61], v[60:61], v[0:1] op_sel_hi:[1,0]
	v_pk_mul_f32 v[58:59], v[58:59], v[0:1] op_sel_hi:[1,0]
	v_pk_mul_f32 v[56:57], v[56:57], v[0:1] op_sel_hi:[1,0]
	v_pk_mul_f32 v[54:55], v[54:55], v[0:1] op_sel_hi:[1,0]
	v_pk_mul_f32 v[52:53], v[52:53], v[0:1] op_sel_hi:[1,0]
	v_pk_mul_f32 v[50:51], v[50:51], v[0:1] op_sel_hi:[1,0]
	v_pk_mul_f32 v[48:49], v[48:49], v[0:1] op_sel_hi:[1,0]

; DI float fexp2(float x) { return __builtin_amdgcn_exp2f(x); }
; DI float mx2(float a, float b) { return __builtin_elementwise_maximum(a, b); }
; DI float hmax(float v) { auto rr = __builtin_amdgcn_permlane32_swap(__float_as_uint(v), __float_as_uint(v), false, false); return mx2(__uint_as_float(rr[0]), __uint_as_float(rr[1])); }
; DI void attn_core2(const u16* __restrict__ P, size_t tokbase, int kcol, int vcol, int n1, int n2, int xs0, bool win, int tq0,
;                    float m0, float l0, const bf16x8 (&qreg)[2][4], f32x16 (&o)[2][2], float (&lsum)[2], char* lds) {
;     ...
;         float mloc = mx2(pt[qs][0], pt[qs][1]);
; #pragma unroll
;         for (int reg = 2; reg < 16; reg += 2) mloc = mx2(mx2(mloc, pt[qs][reg]), pt[qs][reg + 1]);
;         mloc = hmax(mloc) - m[qs];
;         if (__builtin_amdgcn_ballot_w64(mloc > THR) != 0) {
;           const float d = fmaxf(mloc, 0.f);
;           const float alpha = fexp2(-d);
;           m[qs] += d; l[qs] *= alpha; mz[qs] = false;
; #pragma unroll
;           for (int b = 0; b < 2; ++b)
; #pragma unroll
;             for (int reg = 0; reg < 16; ++reg) o[qs][b][reg] *= alpha;
;         }
;         float la = 0.f;
;         if (mz[qs]) {
; #pragma unroll
;           for (int reg = 0; reg < 16; ++reg) { const float e = fexp2(pt[qs][reg]); pt[qs][reg] = e; la += e; }
;         } else {
; #pragma unroll
;           for (int reg = 0; reg < 16; ++reg) { const float e = fexp2(pt[qs][reg] - m[qs]); pt[qs][reg] = e; la += e; }
;         }
;         l[qs] += la;
.LBB0_120:
	v_add_f32_e32 v112, v187, v186
	v_add_f32_e32 v112, v188, v112
	v_add_f32_e32 v112, v189, v112
	v_add_f32_e32 v112, v214, v112
	v_maximum3_f32 v113, v96, v97, v97
	v_add_f32_e32 v112, v215, v112
	v_maximum3_f32 v113, v113, v98, v99
	v_add_f32_e32 v112, v216, v112
	v_maximum3_f32 v113, v113, v100, v101
	v_add_f32_e32 v112, v217, v112
	v_maximum3_f32 v113, v113, v102, v103
	v_add_f32_e32 v112, v218, v112
	v_maximum3_f32 v113, v113, v104, v105
	v_add_f32_e32 v112, v219, v112
	v_maximum3_f32 v113, v113, v106, v107
	v_add_f32_e32 v112, v220, v112
	v_maximum3_f32 v113, v113, v108, v109
	v_add_f32_e32 v112, v221, v112
	v_maximum3_f32 v113, v113, v110, v111
	v_add_f32_e32 v112, v222, v112
	v_mov_b32_e32 v114, v113
	v_add_f32_e32 v112, v223, v112
	s_nop 0
	v_permlane32_swap_b32_e32 v113, v114
	v_add_f32_e32 v112, v224, v112
	v_maximum3_f32 v113, v113, v114, v114
	v_add_f32_e32 v112, v225, v112
	v_sub_f32_e32 v113, v113, v174
	v_add_f32_e32 v112, v185, v112
	v_cmp_lt_f32_e32 vcc, s76, v113
	s_cbranch_vccz .LBB0_122
	v_max_f32_e32 v113, v113, v113
	v_max_f32_e32 v113, 0, v113
	v_exp_f32_e64 v114, -v113
	v_add_f32_e32 v174, v174, v113
	v_mul_f32_e32 v112, v112, v114
	v_pk_mul_f32 v[46:47], v[46:47], v[114:115] op_sel_hi:[1,0]
	v_pk_mul_f32 v[44:45], v[44:45], v[114:115] op_sel_hi:[1,0]
	v_pk_mul_f32 v[42:43], v[42:43], v[114:115] op_sel_hi:[1,0]
	v_pk_mul_f32 v[40:41], v[40:41], v[114:115] op_sel_hi:[1,0]
	v_pk_mul_f32 v[38:39], v[38:39], v[114:115] op_sel_hi:[1,0]
	v_pk_mul_f32 v[36:37], v[36:37], v[114:115] op_sel_hi:[1,0]
	v_pk_mul_f32 v[34:35], v[34:35], v[114:115] op_sel_hi:[1,0]
	v_pk_mul_f32 v[32:33], v[32:33], v[114:115] op_sel_hi:[1,0]
	v_pk_mul_f32 v[30:31], v[30:31], v[114:115] op_sel_hi:[1,0]
	v_pk_mul_f32 v[28:29], v[28:29], v[114:115] op_sel_hi:[1,0]
	v_pk_mul_f32 v[26:27], v[26:27], v[114:115] op_sel_hi:[1,0]
	v_pk_mul_f32 v[24:25], v[24:25], v[114:115] op_sel_hi:[1,0]
	v_pk_mul_f32 v[22:23], v[22:23], v[114:115] op_sel_hi:[1,0]
	v_pk_mul_f32 v[20:21], v[20:21], v[114:115] op_sel_hi:[1,0]
	v_pk_mul_f32 v[18:19], v[18:19], v[114:115] op_sel_hi:[1,0]
	v_pk_mul_f32 v[16:17], v[16:17], v[114:115] op_sel_hi:[1,0]
